# P1 stagger retune: late half runs ctx projection + 3 sleeps before its GEMM stream (was 2)
# baseline (speedup 1.0000x reference)
; __global__ void __launch_bounds__(NTHREADS, 2) fwd_megakernel(Params p) {
;     ...
;         { const int nsl = ((F.bx >> P1_SHIFT) & P1_GROUPS) * P1_STAGGER; for (int i = 0; i < nsl; ++i) __builtin_amdgcn_s_sleep(127); }
.LBB0_403:
	s_cmp_eq_u32 s98, 1
	s_cbranch_scc1 .Lmy_p1_tail
	s_and_b32 s4, s2, 8
	s_bitcmp1_b32 s2, 3
	s_cselect_b64 s[36:37], -1, 0
	s_cmp_eq_u32 s4, 0
	s_mov_b64 s[4:5], 0
	s_cbranch_scc1 .LBB0_405
	s_mov_b64 s[4:5], 13
	s_sleep 0x7f
	s_sleep 0x7f
	s_sleep 0x7f
